# GQA attention main loop rewritten: persistent C-init tuples per head, in-place exp, scalar-add row sums, short max chains, first-tile peeled
# speedup vs baseline: 1.0596x; 1.0098x over previous
; #define LAS __attribute__((address_space(3)))
; __device__ __forceinline__ void attn_core_gqa2(LAS unsigned char* lds, const bf16* __restrict__ Qw, const bf16* __restrict__ Kg, const bf16* __restrict__ Vtg,
;                                                int N, f32x16 (&o)[2][2], const int wave_s) {
;     const int tid = my_tid(wave_s);
;     const int lane = tid & 63, r32 = lane & 31, hi = lane >> 5;
;     constexpr int KW = 64, KBYTES = 64 * KW * 2, BUF = KBYTES + 64 * 128;
;     constexpr float THR = 8.f;
;     const int NT = N / 64;
;     const int krow = tid >> 3, kch = tid & 7, vrow = tid >> 3, vch = tid & 7;
;     LAS unsigned char* const kdst = lds + krow * 128 + ((kch ^ ((krow >> 1) & 7)) * 16);
;     const int vsx = (vrow >> 1) & 7;
;     LAS unsigned char* const vdst0 = lds + KBYTES + vrow * 128 + (((vch & ~1) ^ vsx) * 16) + (vch & 1) * 8;
;     LAS unsigned char* const vdst1 = lds + KBYTES + vrow * 128 + (((vch | 1) ^ vsx) * 16) + (vch & 1) * 8;
;     const bf16* ksrc = Kg + (size_t)krow * ZLD + kch * 8;
;     const bf16* vsrc = Vtg + (size_t)vrow * (size_t)N + vch * 8;
;     u32x4 kreg = *(const GAS u32x4*)ksrc, vreg = *(const GAS u32x4*)vsrc;
;     bf16x8 qr[2][4];
; #pragma unroll
;     for (int h = 0; h < 2; ++h)
; #pragma unroll
;         for (int d0 = 0; d0 < 4; ++d0) qr[h][d0] = *(const GAS bf16x8*)(Qw + (size_t)r32 * ZLD + h * 64 + d0 * 16 + hi * 8);
;     LAS float* wsf = (LAS float*)(lds + WSF_OFF) + (tid >> 6) * 32;
;     const LAS unsigned char* kaddr[4]; const LAS unsigned char* vaddr[4];
; #pragma unroll
; __device__ __forceinline__ void attn_unit_gqa(int xq, int u, LAS unsigned char* lds, const bf16* Z, const bf16* VtB, bf16* OAB, const LAS float* btabs, const int wave) {
;     const int tid = my_tid(wave);
;     const int lane = tid & 63, r32 = lane & 31, hi = lane >> 5;
;     int N, tok0, qb; const int hd = xq & 1;
;     if (u < 64) { N = NP; tok0 = (xq >> 1) * NP; qb = u; }
;     else        { N = NS; tok0 = MC_P + (xq >> 1) * NS; qb = u - 64; }
;     const int hp = wave >> 2, rg = wave & 3, q0w = qb * 128 + rg * 32;
;     const bf16* Qw = Z + (size_t)(tok0 + q0w) * ZLD + 1536 + hd * 256 + hp * 128;
;     const bf16* Kg = Z + (size_t)tok0 * ZLD + 2048 + hd * 64;
;     const bf16* Vt = VtB + (size_t)tok0 * 128 + (size_t)(hd * 64) * N;
;     f32x16 o[2][2];
;     attn_core_gqa2(lds, Qw, Kg, Vt, N, o, wave);
.LBB0_299:
	s_or_b64 exec, exec, s[4:5]
	v_mov_b32_e32 v0, s21
	s_waitcnt lgkmcnt(0)
	s_barrier
	ds_read_b32 v0, v0
	s_movk_i32 s4, 0x5f
	s_waitcnt lgkmcnt(0)
	v_cmp_lt_i32_e32 vcc, s4, v0
	v_readfirstlane_b32 s14, v0
	s_mov_b64 s[4:5], -1
	s_cbranch_vccnz .LBB0_296
	s_lshl_b32 s4, s14, 7
	s_add_i32 s5, s4, 0xffffe000
	s_cmp_lt_i32 s14, 64
	s_cselect_b32 s4, s4, s5
	s_cselect_b32 s45, s35, s34
	s_cselect_b32 s41, 0x80, 64
	s_cselect_b32 s54, 13, 12
	s_or_b32 s4, s4, s86
	s_add_i32 s14, s4, s45
	s_ashr_i32 s15, s14, 31
	s_mul_i32 s4, s14, 0x1200
	s_mul_hi_i32 s5, s14, 0x1200
	s_add_u32 s4, s37, s4
	s_mul_i32 s72, s45, 0x1200
	s_addc_u32 s5, s40, s5
	s_add_u32 s16, s19, s72
	s_addc_u32 s17, s22, 0
	s_lshl_b32 s46, s36, 1
	s_add_u32 s16, s16, s46
	s_addc_u32 s17, s17, 0
	s_add_u32 s16, s16, 0x1000
	s_addc_u32 s17, s17, 0
	s_lshl_b32 s55, s45, 8
	v_mov_b32_e32 v220, v214
	s_add_u32 s45, s25, s55
	v_mov_b32_e32 v8, v214
	s_addc_u32 s47, s26, 0
	s_lshl_b32 s46, s36, s54
	s_lshl_b32 s58, s46, 1
	v_ashrrev_i32_e32 v0, 3, v8
	v_ashrrev_i32_e32 v1, 31, v0
	s_add_u32 s46, s45, s58
	v_and_b32_e32 v11, 7, v8
	v_mov_b64_e32 v[2:3], s[16:17]
	v_lshlrev_b64 v[4:5], s54, v[0:1]
	s_addc_u32 s47, s47, 0
	v_and_b32_e32 v9, 31, v8
	v_mad_i64_i32 v[2:3], s[16:17], v0, s93, v[2:3]
	v_lshlrev_b32_e32 v184, 4, v11
	v_lshlrev_b64 v[4:5], 1, v[4:5]
	v_lshl_add_u64 v[2:3], v[2:3], 0, v[184:185]
	v_lshl_add_u64 v[6:7], s[46:47], 0, v[4:5]
	v_mul_u32_u24_e32 v1, 0x900, v9
	v_bfe_u32 v10, v8, 5, 1
	v_lshl_add_u64 v[6:7], v[6:7], 0, v[184:185]
	global_load_dwordx4 v[120:123], v[2:3], off
	global_load_dwordx4 v[148:151], v[6:7], off
	v_lshlrev_b32_e32 v2, 1, v1
	v_mov_b32_e32 v3, v185
	v_lshl_add_u64 v[2:3], s[4:5], 0, v[2:3]
	v_lshlrev_b32_e32 v6, 4, v10
	v_mov_b32_e32 v7, v185
	v_lshl_add_u64 v[2:3], v[2:3], 0, v[6:7]
	global_load_dwordx4 v[112:115], v[2:3], off offset:3072
	global_load_dwordx4 v[116:119], v[2:3], off offset:3104
	global_load_dwordx4 v[124:127], v[2:3], off offset:3136
	global_load_dwordx4 v[128:131], v[2:3], off offset:3168
	global_load_dwordx4 v[132:135], v[2:3], off offset:3200
	global_load_dwordx4 v[136:139], v[2:3], off offset:3232
	global_load_dwordx4 v[140:143], v[2:3], off offset:3264
	global_load_dwordx4 v[144:147], v[2:3], off offset:3296
	v_lshrrev_b32_e32 v2, 4, v8
	v_bitop3_b32 v7, v2, v8, 7 bitop3:0x28
	v_lshlrev_b32_e32 v16, 4, v7
	v_and_b32_e32 v7, 6, v8
	v_lshl_add_u32 v17, v0, 7, 0
	v_bitop3_b32 v2, v2, v7, 7 bitop3:0x6c
	v_lshrrev_b32_e32 v1, 5, v8
	v_lshl_add_u32 v20, v2, 4, v17
	v_bfe_u32 v2, v8, 1, 3
	v_bitop3_b32 v1, v1, v2, 1 bitop3:0x6c
	v_bfe_u32 v3, v8, 4, 3
	v_lshlrev_b32_e32 v22, 4, v1
	v_bitop3_b32 v1, v10, v2, 2 bitop3:0x36
	v_bitop3_b32 v3, v11, v3, 1 bitop3:0x36
	v_lshlrev_b32_e32 v23, 4, v1
	v_bitop3_b32 v1, v10, v2, 4 bitop3:0x36
	v_lshl_add_u32 v19, v3, 4, v17
	v_lshlrev_b32_e32 v24, 4, v1
	v_bitop3_b32 v1, v10, v2, 6 bitop3:0x36
	v_lshl_add_u64 v[2:3], v[192:193], 0, s[72:73]
	v_mad_i64_i32 v[194:195], s[4:5], v0, s93, v[2:3]
	s_add_u32 s4, s24, s58
	v_lshlrev_b32_e32 v25, 4, v1
	v_lshlrev_b32_e32 v1, 1, v8
	s_addc_u32 s5, s23, 0
	v_lshlrev_b32_e32 v7, 3, v8
	v_and_b32_e32 v1, 0xffffff80, v1
	s_add_u32 s4, s4, s55
	v_and_b32_e32 v18, 8, v7
	v_lshl_add_u32 v21, v9, 7, 0
	v_add_u32_e32 v1, s96, v1
	s_addc_u32 s5, s5, 0
	v_mov_b32_e32 v14, v185
	v_mov_b32_e32 v15, v185
	v_lshl_add_u32 v222, v9, 2, v1
	v_add_u32_e32 v221, v1, v6
	v_lshl_add_u64 v[196:197], s[4:5], 0, v[4:5]
	v_mov_b32_e32 v0, v185
	v_mov_b32_e32 v1, v185
	v_mov_b32_e32 v2, v185
	v_mov_b32_e32 v3, v185
	v_mov_b32_e32 v4, v185
	v_mov_b32_e32 v5, v185
	v_mov_b32_e32 v6, v185
	v_mov_b32_e32 v7, v185
	v_mov_b32_e32 v8, v185
	v_mov_b32_e32 v9, v185
	v_mov_b32_e32 v10, v185
	v_mov_b32_e32 v11, v185
	v_mov_b32_e32 v12, v185
	v_mov_b32_e32 v13, v185
	v_add_u32_e32 v224, v17, v16
	v_add_u32_e32 v225, v20, v18
	v_add_u32_e32 v226, v19, v18
	v_add_u32_e32 v227, v21, v22
	v_add_u32_e32 v228, v21, v23
	v_add_u32_e32 v229, v21, v24
	v_add_u32_e32 v230, v21, v25
	v_mov_b64_e32 v[30:31], v[14:15]
	v_mov_b64_e32 v[46:47], v[14:15]
	v_mov_b64_e32 v[62:63], v[14:15]
	s_mov_b32 s45, 2
	v_mov_b32_e32 v223, 0
	v_mov_b64_e32 v[28:29], v[12:13]
	v_mov_b64_e32 v[26:27], v[10:11]
	v_mov_b64_e32 v[24:25], v[8:9]
	v_mov_b64_e32 v[22:23], v[6:7]
	v_mov_b64_e32 v[20:21], v[4:5]
	v_mov_b64_e32 v[18:19], v[2:3]
	v_mov_b64_e32 v[16:17], v[0:1]
	v_mov_b64_e32 v[44:45], v[12:13]
	v_mov_b64_e32 v[42:43], v[10:11]
	v_mov_b64_e32 v[40:41], v[8:9]
	v_mov_b64_e32 v[38:39], v[6:7]
	v_mov_b64_e32 v[36:37], v[4:5]
	v_mov_b64_e32 v[34:35], v[2:3]
	v_mov_b64_e32 v[32:33], v[0:1]
	v_mov_b64_e32 v[60:61], v[12:13]
	v_mov_b64_e32 v[58:59], v[10:11]
	v_mov_b64_e32 v[56:57], v[8:9]
	v_mov_b64_e32 v[54:55], v[6:7]
	v_mov_b64_e32 v[52:53], v[4:5]
	v_mov_b64_e32 v[50:51], v[2:3]
	v_mov_b64_e32 v[48:49], v[0:1]
	v_mov_b32_e32 v231, 0
	v_mov_b32_e32 v202, 0
	v_mov_b32_e32 v173, 0
	v_mov_b32_e32 v152, 0
	v_mov_b32_e32 v153, 0
	v_mov_b32_e32 v154, 0
	v_mov_b32_e32 v155, 0
	v_mov_b32_e32 v156, 0
	v_mov_b32_e32 v157, 0
	v_mov_b32_e32 v158, 0
	v_mov_b32_e32 v159, 0
	v_mov_b32_e32 v160, 0
	v_mov_b32_e32 v161, 0
	v_mov_b32_e32 v162, 0
	v_mov_b32_e32 v163, 0
	v_mov_b32_e32 v164, 0
	v_mov_b32_e32 v165, 0
	v_mov_b32_e32 v166, 0
	v_mov_b32_e32 v167, 0
	v_mov_b32_e32 v250, 0
	v_mov_b32_e32 v168, 0
	v_mov_b32_e32 v169, 0
	v_mov_b32_e32 v170, 0
	v_mov_b32_e32 v171, 0
	v_mov_b32_e32 v172, 0
	v_mov_b32_e32 v173, 0
	v_mov_b32_e32 v174, 0
	v_mov_b32_e32 v175, 0
	v_mov_b32_e32 v176, 0
	v_mov_b32_e32 v177, 0
	v_mov_b32_e32 v178, 0
	v_mov_b32_e32 v179, 0
	v_mov_b32_e32 v180, 0
	v_mov_b32_e32 v181, 0
	v_mov_b32_e32 v182, 0
	v_mov_b32_e32 v183, 0
	v_mov_b32_e32 v251, 0
	s_branch .LBB0_302
.LBB0_302:
	s_waitcnt vmcnt(1)
	ds_write_b128 v224, v[120:123]
	s_waitcnt vmcnt(0)
	ds_write_b64 v225, v[148:149] offset:8192
	ds_write_b64 v226, v[150:151] offset:8192
	s_waitcnt lgkmcnt(0)
	s_barrier
	ds_read_b128 v[96:99], v227
	ds_read_b128 v[100:103], v228
	ds_read_b128 v[104:107], v229
	ds_read_b128 v[108:111], v230
	ds_read_b128 v[198:201], v227 offset:4096
	ds_read_b128 v[202:205], v228 offset:4096
	ds_read_b128 v[206:209], v229 offset:4096
	ds_read_b128 v[210:213], v230 offset:4096
	s_waitcnt lgkmcnt(7)
	v_mfma_f32_32x32x16_bf16 v[80:95], v[96:99], v[112:115], v[152:167]
	s_waitcnt lgkmcnt(6)
	v_mfma_f32_32x32x16_bf16 v[80:95], v[100:103], v[116:119], v[80:95]
	s_waitcnt lgkmcnt(5)
	v_mfma_f32_32x32x16_bf16 v[80:95], v[104:107], v[124:127], v[80:95]
	s_waitcnt lgkmcnt(4)
	v_mfma_f32_32x32x16_bf16 v[80:95], v[108:111], v[128:131], v[80:95]
	v_mfma_f32_32x32x16_bf16 v[64:79], v[96:99], v[132:135], v[168:183]
	v_mfma_f32_32x32x16_bf16 v[64:79], v[100:103], v[136:139], v[64:79]
	v_mfma_f32_32x32x16_bf16 v[64:79], v[104:107], v[140:143], v[64:79]
	v_mfma_f32_32x32x16_bf16 v[64:79], v[108:111], v[144:147], v[64:79]
	s_add_i32 s4, s45, -1
	s_cmp_ge_u32 s4, s41
	s_cbranch_scc1 .Lgq_nold1
	v_lshl_add_u64 v[248:249], v[194:195], 0, v[184:185]
	v_add_co_u32_e32 v248, vcc, 0x16049000, v248
	s_nop 1
	v_addc_co_u32_e32 v249, vcc, 0, v249, vcc
	global_load_dwordx4 v[120:123], v[248:249], off
	v_lshl_add_u64 v[248:249], v[196:197], 0, v[184:185]
	v_add_co_u32_e32 v248, vcc, 0x32800000, v248
	s_nop 1
	v_addc_co_u32_e32 v249, vcc, 0, v249, vcc
	global_load_dwordx4 v[148:151], v[248:249], off offset:128
.Lgq_nold1:
	ds_read_b128 v[232:235], v227 offset:8192
	ds_read_b128 v[236:239], v227 offset:12288
	ds_read_b128 v[240:243], v228 offset:8192
	ds_read_b128 v[244:247], v228 offset:12288
	v_max3_f32 v252, v80, v81, v82
	v_max3_f32 v252, v252, v83, v84
	v_max3_f32 v252, v252, v85, v86
	v_max3_f32 v252, v252, v87, v88
	v_max3_f32 v252, v252, v89, v90
	v_max3_f32 v252, v252, v91, v92
	v_max3_f32 v252, v252, v93, v94
	v_max_f32_e32 v252, v252, v95
	v_mov_b32_e32 v248, v252
	s_nop 1
	v_permlane32_swap_b32_e32 v252, v248
	v_max_f32_e32 v252, v252, v248
	v_max3_f32 v253, v64, v65, v66
	v_max3_f32 v253, v253, v67, v68
	v_max3_f32 v253, v253, v69, v70
	v_max3_f32 v253, v253, v71, v72
	v_max3_f32 v253, v253, v73, v74
	v_max3_f32 v253, v253, v75, v76
	v_max3_f32 v253, v253, v77, v78
	v_max_f32_e32 v253, v253, v79
	v_mov_b32_e32 v249, v253
	s_nop 1
	v_permlane32_swap_b32_e32 v253, v249
	v_max_f32_e32 v253, v253, v249
	v_mov_b32_e32 v231, v252
	v_sub_f32_e32 v80, v80, v252
	v_sub_f32_e32 v81, v81, v252
	v_sub_f32_e32 v82, v82, v252
	v_sub_f32_e32 v83, v83, v252
	v_sub_f32_e32 v84, v84, v252
	v_sub_f32_e32 v85, v85, v252
	v_sub_f32_e32 v86, v86, v252
	v_sub_f32_e32 v87, v87, v252
	v_sub_f32_e32 v88, v88, v252
	v_sub_f32_e32 v89, v89, v252
	v_sub_f32_e32 v90, v90, v252
	v_sub_f32_e32 v91, v91, v252
	v_sub_f32_e32 v92, v92, v252
	v_sub_f32_e32 v93, v93, v252
	v_sub_f32_e32 v94, v94, v252
	v_sub_f32_e32 v95, v95, v252
	v_xor_b32_e32 v152, 0x80000000, v231
	v_mov_b32_e32 v153, v152
	v_mov_b32_e32 v154, v152
	v_mov_b32_e32 v155, v152
	v_mov_b32_e32 v156, v152
	v_mov_b32_e32 v157, v152
	v_mov_b32_e32 v158, v152
	v_mov_b32_e32 v159, v152
	v_mov_b32_e32 v160, v152
	v_mov_b32_e32 v161, v152
	v_mov_b32_e32 v162, v152
	v_mov_b32_e32 v163, v152
	v_mov_b32_e32 v164, v152
	v_mov_b32_e32 v165, v152
	v_mov_b32_e32 v166, v152
	v_mov_b32_e32 v167, v152
	v_mov_b32_e32 v223, v253
	v_sub_f32_e32 v64, v64, v253
	v_sub_f32_e32 v65, v65, v253
	v_sub_f32_e32 v66, v66, v253
	v_sub_f32_e32 v67, v67, v253
	v_sub_f32_e32 v68, v68, v253
	v_sub_f32_e32 v69, v69, v253
	v_sub_f32_e32 v70, v70, v253
	v_sub_f32_e32 v71, v71, v253
	v_sub_f32_e32 v72, v72, v253
	v_sub_f32_e32 v73, v73, v253
	v_sub_f32_e32 v74, v74, v253
	v_sub_f32_e32 v75, v75, v253
	v_sub_f32_e32 v76, v76, v253
	v_sub_f32_e32 v77, v77, v253
	v_sub_f32_e32 v78, v78, v253
	v_sub_f32_e32 v79, v79, v253
	v_xor_b32_e32 v168, 0x80000000, v223
	v_mov_b32_e32 v169, v168
	v_mov_b32_e32 v170, v168
	v_mov_b32_e32 v171, v168
	v_mov_b32_e32 v172, v168
	v_mov_b32_e32 v173, v168
	v_mov_b32_e32 v174, v168
	v_mov_b32_e32 v175, v168
	v_mov_b32_e32 v176, v168
	v_mov_b32_e32 v177, v168
	v_mov_b32_e32 v178, v168
	v_mov_b32_e32 v179, v168
	v_mov_b32_e32 v180, v168
	v_mov_b32_e32 v181, v168
	v_mov_b32_e32 v182, v168
	v_mov_b32_e32 v183, v168
	v_exp_f32_e32 v80, v80
	v_exp_f32_e32 v81, v81
	v_exp_f32_e32 v82, v82
	v_exp_f32_e32 v83, v83
	v_exp_f32_e32 v84, v84
	v_exp_f32_e32 v85, v85
	v_exp_f32_e32 v86, v86
	v_exp_f32_e32 v87, v87
	v_exp_f32_e32 v88, v88
	v_exp_f32_e32 v89, v89
	v_exp_f32_e32 v90, v90
	v_exp_f32_e32 v91, v91
	v_exp_f32_e32 v92, v92
	v_exp_f32_e32 v93, v93
	v_exp_f32_e32 v94, v94
	v_exp_f32_e32 v95, v95
	v_add_f32_e32 v104, v80, v81
	v_add_f32_e32 v105, v82, v83
	v_add_f32_e32 v106, v84, v85
	v_add_f32_e32 v107, v86, v87
	v_add_f32_e32 v108, v88, v89
	v_add_f32_e32 v109, v90, v91
	v_add_f32_e32 v110, v92, v93
	v_add_f32_e32 v111, v94, v95
	v_add_f32_e32 v104, v104, v105
	v_add_f32_e32 v106, v106, v107
	v_add_f32_e32 v108, v108, v109
	v_add_f32_e32 v110, v110, v111
	v_add_f32_e32 v104, v104, v106
	v_add_f32_e32 v108, v108, v110
	v_add_f32_e32 v104, v104, v108
	v_add_f32_e32 v250, v250, v104
	v_cvt_pk_bf16_f32 v96, v80, v81
	v_cvt_pk_bf16_f32 v97, v82, v83
	v_cvt_pk_bf16_f32 v98, v84, v85
	v_cvt_pk_bf16_f32 v99, v86, v87
	v_cvt_pk_bf16_f32 v100, v88, v89
	v_cvt_pk_bf16_f32 v101, v90, v91
	v_cvt_pk_bf16_f32 v102, v92, v93
	v_cvt_pk_bf16_f32 v103, v94, v95
	v_exp_f32_e32 v64, v64
	v_exp_f32_e32 v65, v65
	v_exp_f32_e32 v66, v66
	v_exp_f32_e32 v67, v67
	v_exp_f32_e32 v68, v68
	v_exp_f32_e32 v69, v69
	v_exp_f32_e32 v70, v70
	v_exp_f32_e32 v71, v71
	v_exp_f32_e32 v72, v72
	v_exp_f32_e32 v73, v73
	v_exp_f32_e32 v74, v74
	v_exp_f32_e32 v75, v75
	v_exp_f32_e32 v76, v76
	v_exp_f32_e32 v77, v77
	v_exp_f32_e32 v78, v78
	v_exp_f32_e32 v79, v79
	v_add_f32_e32 v104, v64, v65
	v_add_f32_e32 v105, v66, v67
	v_add_f32_e32 v106, v68, v69
	v_add_f32_e32 v107, v70, v71
	v_add_f32_e32 v108, v72, v73
	v_add_f32_e32 v109, v74, v75
	v_add_f32_e32 v110, v76, v77
	v_add_f32_e32 v111, v78, v79
	v_add_f32_e32 v104, v104, v105
	v_add_f32_e32 v106, v106, v107
	v_add_f32_e32 v108, v108, v109
	v_add_f32_e32 v110, v110, v111
	v_add_f32_e32 v104, v104, v106
	v_add_f32_e32 v108, v108, v110
	v_add_f32_e32 v104, v104, v108
	v_add_f32_e32 v251, v251, v104
	v_cvt_pk_bf16_f32 v104, v64, v65
	v_cvt_pk_bf16_f32 v105, v66, v67
	v_cvt_pk_bf16_f32 v106, v68, v69
	v_cvt_pk_bf16_f32 v107, v70, v71
	v_cvt_pk_bf16_f32 v108, v72, v73
	v_cvt_pk_bf16_f32 v109, v74, v75
	v_cvt_pk_bf16_f32 v110, v76, v77
	v_cvt_pk_bf16_f32 v111, v78, v79
	s_waitcnt lgkmcnt(7)
	v_mfma_f32_32x32x16_bf16 v[80:95], v[198:201], v[112:115], v[152:167]
	s_waitcnt lgkmcnt(6)
	v_mfma_f32_32x32x16_bf16 v[80:95], v[202:205], v[116:119], v[80:95]
	s_waitcnt lgkmcnt(5)
	v_mfma_f32_32x32x16_bf16 v[80:95], v[206:209], v[124:127], v[80:95]
	s_waitcnt lgkmcnt(4)
	v_mfma_f32_32x32x16_bf16 v[80:95], v[210:213], v[128:131], v[80:95]
	v_mfma_f32_32x32x16_bf16 v[64:79], v[198:201], v[132:135], v[168:183]
	v_mfma_f32_32x32x16_bf16 v[64:79], v[202:205], v[136:139], v[64:79]
	v_mfma_f32_32x32x16_bf16 v[64:79], v[206:209], v[140:143], v[64:79]
	v_mfma_f32_32x32x16_bf16 v[64:79], v[210:213], v[144:147], v[64:79]
	s_waitcnt lgkmcnt(3)
	v_mfma_f32_32x32x16_bf16 v[48:63], v[96:99], v[232:235], v[48:63]
	s_waitcnt lgkmcnt(2)
	v_mfma_f32_32x32x16_bf16 v[32:47], v[96:99], v[236:239], v[32:47]
	v_mfma_f32_32x32x16_bf16 v[16:31], v[104:107], v[232:235], v[16:31]
	v_mfma_f32_32x32x16_bf16 v[0:15], v[104:107], v[236:239], v[0:15]
	s_nop 1
	v_max3_f32 v252, v80, v81, v82
	v_max3_f32 v252, v252, v83, v84
	v_max3_f32 v252, v252, v85, v86
	v_max3_f32 v252, v252, v87, v88
	v_max3_f32 v252, v252, v89, v90
	v_max3_f32 v252, v252, v91, v92
	v_max3_f32 v252, v252, v93, v94
	v_max_f32_e32 v252, v252, v95
	v_mov_b32_e32 v248, v252
	s_nop 1
	v_permlane32_swap_b32_e32 v252, v248
	v_max_f32_e32 v252, v252, v248
	s_waitcnt lgkmcnt(1)
	v_mfma_f32_32x32x16_bf16 v[48:63], v[100:103], v[240:243], v[48:63]
	s_waitcnt lgkmcnt(0)
	v_mfma_f32_32x32x16_bf16 v[32:47], v[100:103], v[244:247], v[32:47]
	v_mfma_f32_32x32x16_bf16 v[16:31], v[108:111], v[240:243], v[16:31]
	v_mfma_f32_32x32x16_bf16 v[0:15], v[108:111], v[244:247], v[0:15]
	ds_read_b128 v[232:235], v229 offset:8192
	ds_read_b128 v[236:239], v229 offset:12288
	ds_read_b128 v[240:243], v230 offset:8192
	ds_read_b128 v[244:247], v230 offset:12288
	v_max3_f32 v253, v64, v65, v66
	v_max3_f32 v253, v253, v67, v68
	v_max3_f32 v253, v253, v69, v70
	v_max3_f32 v253, v253, v71, v72
	v_max3_f32 v253, v253, v73, v74
	v_max3_f32 v253, v253, v75, v76
	v_max3_f32 v253, v253, v77, v78
	v_max_f32_e32 v253, v253, v79
	v_mov_b32_e32 v249, v253
	s_nop 1
	v_permlane32_swap_b32_e32 v253, v249
	v_max_f32_e32 v253, v253, v249
	v_cmp_lt_f32_e32 vcc, s97, v252
	s_cbranch_vccnz .Lgq_rare3
.Lgq_back2:
	v_cmp_lt_f32_e32 vcc, s97, v253
	s_cbranch_vccnz .Lgq_rare5
.Lgq_back4:
	v_exp_f32_e32 v80, v80
	v_exp_f32_e32 v81, v81
	v_exp_f32_e32 v82, v82
	v_exp_f32_e32 v83, v83
	v_exp_f32_e32 v84, v84
	v_exp_f32_e32 v85, v85
	v_exp_f32_e32 v86, v86
	v_exp_f32_e32 v87, v87
	v_exp_f32_e32 v88, v88
	v_exp_f32_e32 v89, v89
	v_exp_f32_e32 v90, v90
	v_exp_f32_e32 v91, v91
	v_exp_f32_e32 v92, v92
	v_exp_f32_e32 v93, v93
	v_exp_f32_e32 v94, v94
	v_exp_f32_e32 v95, v95
	v_add_f32_e32 v206, v80, v81
	v_add_f32_e32 v207, v82, v83
	v_add_f32_e32 v208, v84, v85
	v_add_f32_e32 v209, v86, v87
	v_add_f32_e32 v210, v88, v89
	v_add_f32_e32 v211, v90, v91
	v_add_f32_e32 v212, v92, v93
	v_add_f32_e32 v213, v94, v95
	v_add_f32_e32 v206, v206, v207
	v_add_f32_e32 v208, v208, v209
	v_add_f32_e32 v210, v210, v211
	v_add_f32_e32 v212, v212, v213
	v_add_f32_e32 v206, v206, v208
	v_add_f32_e32 v210, v210, v212
	v_add_f32_e32 v206, v206, v210
	v_add_f32_e32 v250, v250, v206
	v_cvt_pk_bf16_f32 v198, v80, v81
	v_cvt_pk_bf16_f32 v199, v82, v83
	v_cvt_pk_bf16_f32 v200, v84, v85
	v_cvt_pk_bf16_f32 v201, v86, v87
	v_cvt_pk_bf16_f32 v202, v88, v89
	v_cvt_pk_bf16_f32 v203, v90, v91
	v_cvt_pk_bf16_f32 v204, v92, v93
	v_cvt_pk_bf16_f32 v205, v94, v95
	v_exp_f32_e32 v64, v64
	v_exp_f32_e32 v65, v65
	v_exp_f32_e32 v66, v66
	v_exp_f32_e32 v67, v67
	v_exp_f32_e32 v68, v68
	v_exp_f32_e32 v69, v69
	v_exp_f32_e32 v70, v70
	v_exp_f32_e32 v71, v71
	v_exp_f32_e32 v72, v72
	v_exp_f32_e32 v73, v73
	v_exp_f32_e32 v74, v74
	v_exp_f32_e32 v75, v75
	v_exp_f32_e32 v76, v76
	v_exp_f32_e32 v77, v77
	v_exp_f32_e32 v78, v78
	v_exp_f32_e32 v79, v79
	v_add_f32_e32 v206, v64, v65
	v_add_f32_e32 v207, v66, v67
	v_add_f32_e32 v208, v68, v69
	v_add_f32_e32 v209, v70, v71
	v_add_f32_e32 v210, v72, v73
	v_add_f32_e32 v211, v74, v75
	v_add_f32_e32 v212, v76, v77
	v_add_f32_e32 v213, v78, v79
	v_add_f32_e32 v206, v206, v207
	v_add_f32_e32 v208, v208, v209
	v_add_f32_e32 v210, v210, v211
	v_add_f32_e32 v212, v212, v213
	v_add_f32_e32 v206, v206, v208
	v_add_f32_e32 v210, v210, v212
	v_add_f32_e32 v206, v206, v210
	v_add_f32_e32 v251, v251, v206
	v_cvt_pk_bf16_f32 v206, v64, v65
	v_cvt_pk_bf16_f32 v207, v66, v67
	v_cvt_pk_bf16_f32 v208, v68, v69
	v_cvt_pk_bf16_f32 v209, v70, v71
	v_cvt_pk_bf16_f32 v210, v72, v73
	v_cvt_pk_bf16_f32 v211, v74, v75
	v_cvt_pk_bf16_f32 v212, v76, v77
	v_cvt_pk_bf16_f32 v213, v78, v79
	s_waitcnt lgkmcnt(3)
	v_mfma_f32_32x32x16_bf16 v[48:63], v[198:201], v[232:235], v[48:63]
	s_waitcnt lgkmcnt(2)
	v_mfma_f32_32x32x16_bf16 v[32:47], v[198:201], v[236:239], v[32:47]
	v_mfma_f32_32x32x16_bf16 v[16:31], v[206:209], v[232:235], v[16:31]
	v_mfma_f32_32x32x16_bf16 v[0:15], v[206:209], v[236:239], v[0:15]
	s_waitcnt lgkmcnt(1)
	v_mfma_f32_32x32x16_bf16 v[48:63], v[202:205], v[240:243], v[48:63]
	s_waitcnt lgkmcnt(0)
	v_mfma_f32_32x32x16_bf16 v[32:47], v[202:205], v[244:247], v[32:47]
	v_mfma_f32_32x32x16_bf16 v[16:31], v[210:213], v[240:243], v[16:31]
	v_mfma_f32_32x32x16_bf16 v[0:15], v[210:213], v[244:247], v[0:15]
	s_waitcnt vmcnt(1)
	ds_write_b128 v224, v[120:123] offset:16384
	s_waitcnt vmcnt(0)
	ds_write_b64 v225, v[148:149] offset:24576
	ds_write_b64 v226, v[150:151] offset:24576
	s_waitcnt lgkmcnt(0)
	s_barrier
	ds_read_b128 v[96:99], v227 offset:16384
	ds_read_b128 v[100:103], v228 offset:16384
	ds_read_b128 v[104:107], v229 offset:16384
	ds_read_b128 v[108:111], v230 offset:16384
	ds_read_b128 v[198:201], v227 offset:20480
	ds_read_b128 v[202:205], v228 offset:20480
	ds_read_b128 v[206:209], v229 offset:20480
	ds_read_b128 v[210:213], v230 offset:20480
	s_waitcnt lgkmcnt(7)
	v_mfma_f32_32x32x16_bf16 v[80:95], v[96:99], v[112:115], v[152:167]
	s_waitcnt lgkmcnt(6)
	v_mfma_f32_32x32x16_bf16 v[80:95], v[100:103], v[116:119], v[80:95]
	s_waitcnt lgkmcnt(5)
	v_mfma_f32_32x32x16_bf16 v[80:95], v[104:107], v[124:127], v[80:95]
	s_waitcnt lgkmcnt(4)
	v_mfma_f32_32x32x16_bf16 v[80:95], v[108:111], v[128:131], v[80:95]
	v_mfma_f32_32x32x16_bf16 v[64:79], v[96:99], v[132:135], v[168:183]
	v_mfma_f32_32x32x16_bf16 v[64:79], v[100:103], v[136:139], v[64:79]
	v_mfma_f32_32x32x16_bf16 v[64:79], v[104:107], v[140:143], v[64:79]
	v_mfma_f32_32x32x16_bf16 v[64:79], v[108:111], v[144:147], v[64:79]
	s_cmp_ge_u32 s45, s41
	s_cbranch_scc1 .Lgq_nold6
	v_lshl_add_u64 v[248:249], v[194:195], 0, v[184:185]
	v_add_co_u32_e32 v248, vcc, 0x16091000, v248
	s_nop 1
	v_addc_co_u32_e32 v249, vcc, 0, v249, vcc
	global_load_dwordx4 v[120:123], v[248:249], off
	v_lshl_add_u64 v[248:249], v[196:197], 0, v[184:185]
	v_add_co_u32_e32 v248, vcc, 0x32800000, v248
	s_nop 1
	v_addc_co_u32_e32 v249, vcc, 0, v249, vcc
	global_load_dwordx4 v[148:151], v[248:249], off offset:256
.Lgq_nold6:
	ds_read_b128 v[232:235], v227 offset:24576
	ds_read_b128 v[236:239], v227 offset:28672
	ds_read_b128 v[240:243], v228 offset:24576
	ds_read_b128 v[244:247], v228 offset:28672
	v_max3_f32 v252, v80, v81, v82
	v_max3_f32 v252, v252, v83, v84
	v_max3_f32 v252, v252, v85, v86
	v_max3_f32 v252, v252, v87, v88
	v_max3_f32 v252, v252, v89, v90
	v_max3_f32 v252, v252, v91, v92
	v_max3_f32 v252, v252, v93, v94
	v_max_f32_e32 v252, v252, v95
	v_mov_b32_e32 v248, v252
	s_nop 1
	v_permlane32_swap_b32_e32 v252, v248
	v_max_f32_e32 v252, v252, v248
	v_max3_f32 v253, v64, v65, v66
	v_max3_f32 v253, v253, v67, v68
	v_max3_f32 v253, v253, v69, v70
	v_max3_f32 v253, v253, v71, v72
	v_max3_f32 v253, v253, v73, v74
	v_max3_f32 v253, v253, v75, v76
	v_max3_f32 v253, v253, v77, v78
	v_max_f32_e32 v253, v253, v79
	v_mov_b32_e32 v249, v253
	s_nop 1
	v_permlane32_swap_b32_e32 v253, v249
	v_max_f32_e32 v253, v253, v249
	v_cmp_lt_f32_e32 vcc, s97, v252
	s_cbranch_vccnz .Lgq_rare8

.Lgq_back9:
	v_exp_f32_e32 v80, v80
	v_exp_f32_e32 v81, v81
	v_exp_f32_e32 v82, v82
	v_exp_f32_e32 v83, v83
	v_exp_f32_e32 v84, v84
	v_exp_f32_e32 v85, v85
	v_exp_f32_e32 v86, v86
	v_exp_f32_e32 v87, v87
	v_exp_f32_e32 v88, v88
	v_exp_f32_e32 v89, v89
	v_exp_f32_e32 v90, v90
	v_exp_f32_e32 v91, v91
	v_exp_f32_e32 v92, v92
	v_exp_f32_e32 v93, v93
	v_exp_f32_e32 v94, v94
	v_exp_f32_e32 v95, v95
	v_add_f32_e32 v104, v80, v81
	v_add_f32_e32 v105, v82, v83
	v_add_f32_e32 v106, v84, v85
	v_add_f32_e32 v107, v86, v87
	v_add_f32_e32 v108, v88, v89
	v_add_f32_e32 v109, v90, v91
	v_add_f32_e32 v110, v92, v93
	v_add_f32_e32 v111, v94, v95
	v_add_f32_e32 v104, v104, v105
	v_add_f32_e32 v106, v106, v107
	v_add_f32_e32 v108, v108, v109
	v_add_f32_e32 v110, v110, v111
	v_add_f32_e32 v104, v104, v106
	v_add_f32_e32 v108, v108, v110
	v_add_f32_e32 v104, v104, v108
	v_add_f32_e32 v250, v250, v104
	v_cvt_pk_bf16_f32 v96, v80, v81
	v_cvt_pk_bf16_f32 v97, v82, v83
	v_cvt_pk_bf16_f32 v98, v84, v85
	v_cvt_pk_bf16_f32 v99, v86, v87
	v_cvt_pk_bf16_f32 v100, v88, v89
	v_cvt_pk_bf16_f32 v101, v90, v91
	v_cvt_pk_bf16_f32 v102, v92, v93
	v_cvt_pk_bf16_f32 v103, v94, v95
	v_exp_f32_e32 v64, v64
	v_exp_f32_e32 v65, v65
	v_exp_f32_e32 v66, v66
	v_exp_f32_e32 v67, v67
	v_exp_f32_e32 v68, v68
	v_exp_f32_e32 v69, v69
	v_exp_f32_e32 v70, v70
	v_exp_f32_e32 v71, v71
	v_exp_f32_e32 v72, v72
	v_exp_f32_e32 v73, v73
	v_exp_f32_e32 v74, v74
	v_exp_f32_e32 v75, v75
	v_exp_f32_e32 v76, v76
	v_exp_f32_e32 v77, v77
	v_exp_f32_e32 v78, v78
	v_exp_f32_e32 v79, v79
	v_add_f32_e32 v104, v64, v65
	v_add_f32_e32 v105, v66, v67
	v_add_f32_e32 v106, v68, v69
	v_add_f32_e32 v107, v70, v71
	v_add_f32_e32 v108, v72, v73
	v_add_f32_e32 v109, v74, v75
	v_add_f32_e32 v110, v76, v77
	v_add_f32_e32 v111, v78, v79
	v_add_f32_e32 v104, v104, v105
	v_add_f32_e32 v106, v106, v107
	v_add_f32_e32 v108, v108, v109
	v_add_f32_e32 v110, v110, v111
	v_add_f32_e32 v104, v104, v106
	v_add_f32_e32 v108, v108, v110
	v_add_f32_e32 v104, v104, v108
	v_add_f32_e32 v251, v251, v104
	v_cvt_pk_bf16_f32 v104, v64, v65
	v_cvt_pk_bf16_f32 v105, v66, v67
	v_cvt_pk_bf16_f32 v106, v68, v69
	v_cvt_pk_bf16_f32 v107, v70, v71
	v_cvt_pk_bf16_f32 v108, v72, v73
	v_cvt_pk_bf16_f32 v109, v74, v75
	v_cvt_pk_bf16_f32 v110, v76, v77
	v_cvt_pk_bf16_f32 v111, v78, v79
	s_waitcnt lgkmcnt(7)
	v_mfma_f32_32x32x16_bf16 v[80:95], v[198:201], v[112:115], v[152:167]
	s_waitcnt lgkmcnt(6)
	v_mfma_f32_32x32x16_bf16 v[80:95], v[202:205], v[116:119], v[80:95]
	s_waitcnt lgkmcnt(5)
	v_mfma_f32_32x32x16_bf16 v[80:95], v[206:209], v[124:127], v[80:95]
	s_waitcnt lgkmcnt(4)
	v_mfma_f32_32x32x16_bf16 v[80:95], v[210:213], v[128:131], v[80:95]
	v_mfma_f32_32x32x16_bf16 v[64:79], v[198:201], v[132:135], v[168:183]
	v_mfma_f32_32x32x16_bf16 v[64:79], v[202:205], v[136:139], v[64:79]
	v_mfma_f32_32x32x16_bf16 v[64:79], v[206:209], v[140:143], v[64:79]
	v_mfma_f32_32x32x16_bf16 v[64:79], v[210:213], v[144:147], v[64:79]
	s_waitcnt lgkmcnt(3)
	v_mfma_f32_32x32x16_bf16 v[48:63], v[96:99], v[232:235], v[48:63]
	s_waitcnt lgkmcnt(2)
	v_mfma_f32_32x32x16_bf16 v[32:47], v[96:99], v[236:239], v[32:47]
	v_mfma_f32_32x32x16_bf16 v[16:31], v[104:107], v[232:235], v[16:31]
	v_mfma_f32_32x32x16_bf16 v[0:15], v[104:107], v[236:239], v[0:15]
	s_nop 1
	v_max3_f32 v252, v80, v81, v82
	v_max3_f32 v252, v252, v83, v84
	v_max3_f32 v252, v252, v85, v86
	v_max3_f32 v252, v252, v87, v88
	v_max3_f32 v252, v252, v89, v90
	v_max3_f32 v252, v252, v91, v92
	v_max3_f32 v252, v252, v93, v94
	v_max_f32_e32 v252, v252, v95
	v_mov_b32_e32 v248, v252
	s_nop 1
	v_permlane32_swap_b32_e32 v252, v248
	v_max_f32_e32 v252, v252, v248
	s_waitcnt lgkmcnt(1)
	v_mfma_f32_32x32x16_bf16 v[48:63], v[100:103], v[240:243], v[48:63]
	s_waitcnt lgkmcnt(0)
	v_mfma_f32_32x32x16_bf16 v[32:47], v[100:103], v[244:247], v[32:47]
	v_mfma_f32_32x32x16_bf16 v[16:31], v[108:111], v[240:243], v[16:31]
	v_mfma_f32_32x32x16_bf16 v[0:15], v[108:111], v[244:247], v[0:15]
	ds_read_b128 v[232:235], v229 offset:24576
	ds_read_b128 v[236:239], v229 offset:28672
	ds_read_b128 v[240:243], v230 offset:24576
	ds_read_b128 v[244:247], v230 offset:28672
	v_max3_f32 v253, v64, v65, v66
	v_max3_f32 v253, v253, v67, v68
	v_max3_f32 v253, v253, v69, v70
	v_max3_f32 v253, v253, v71, v72
	v_max3_f32 v253, v253, v73, v74
	v_max3_f32 v253, v253, v75, v76
	v_max3_f32 v253, v253, v77, v78
	v_max_f32_e32 v253, v253, v79
	v_mov_b32_e32 v249, v253
	s_nop 1
	v_permlane32_swap_b32_e32 v253, v249
	v_max_f32_e32 v253, v253, v249
	v_cmp_lt_f32_e32 vcc, s97, v252
	s_cbranch_vccnz .Lgq_rare12

; __device__ __forceinline__ void attn_core_gqa2(LAS unsigned char* lds, const bf16* __restrict__ Qw, const bf16* __restrict__ Kg, const bf16* __restrict__ Vtg,
;                                                int N, f32x16 (&o)[2][2], const int wave_s) {
;     ...
;     for (int t = 0; t < NT; t += 2) { TILE2(0, t); TILE2(1, t + 1); }
.Lgq_back13:
	v_exp_f32_e32 v80, v80
	v_exp_f32_e32 v81, v81
	v_exp_f32_e32 v82, v82
	v_exp_f32_e32 v83, v83
	v_exp_f32_e32 v84, v84
	v_exp_f32_e32 v85, v85
	v_exp_f32_e32 v86, v86
	v_exp_f32_e32 v87, v87
	v_exp_f32_e32 v88, v88
	v_exp_f32_e32 v89, v89
	v_exp_f32_e32 v90, v90
	v_exp_f32_e32 v91, v91
	v_exp_f32_e32 v92, v92
	v_exp_f32_e32 v93, v93
	v_exp_f32_e32 v94, v94
	v_exp_f32_e32 v95, v95
	v_add_f32_e32 v206, v80, v81
	v_add_f32_e32 v207, v82, v83
	v_add_f32_e32 v208, v84, v85
	v_add_f32_e32 v209, v86, v87
	v_add_f32_e32 v210, v88, v89
	v_add_f32_e32 v211, v90, v91
	v_add_f32_e32 v212, v92, v93
	v_add_f32_e32 v213, v94, v95
	v_add_f32_e32 v206, v206, v207
	v_add_f32_e32 v208, v208, v209
	v_add_f32_e32 v210, v210, v211
	v_add_f32_e32 v212, v212, v213
	v_add_f32_e32 v206, v206, v208
	v_add_f32_e32 v210, v210, v212
	v_add_f32_e32 v206, v206, v210
	v_add_f32_e32 v250, v250, v206
	v_cvt_pk_bf16_f32 v198, v80, v81
	v_cvt_pk_bf16_f32 v199, v82, v83
	v_cvt_pk_bf16_f32 v200, v84, v85
	v_cvt_pk_bf16_f32 v201, v86, v87
	v_cvt_pk_bf16_f32 v202, v88, v89
	v_cvt_pk_bf16_f32 v203, v90, v91
	v_cvt_pk_bf16_f32 v204, v92, v93
	v_cvt_pk_bf16_f32 v205, v94, v95
	v_exp_f32_e32 v64, v64
	v_exp_f32_e32 v65, v65
	v_exp_f32_e32 v66, v66
	v_exp_f32_e32 v67, v67
	v_exp_f32_e32 v68, v68
	v_exp_f32_e32 v69, v69
	v_exp_f32_e32 v70, v70
	v_exp_f32_e32 v71, v71
	v_exp_f32_e32 v72, v72
	v_exp_f32_e32 v73, v73
	v_exp_f32_e32 v74, v74
	v_exp_f32_e32 v75, v75
	v_exp_f32_e32 v76, v76
	v_exp_f32_e32 v77, v77
	v_exp_f32_e32 v78, v78
	v_exp_f32_e32 v79, v79
	v_add_f32_e32 v206, v64, v65
	v_add_f32_e32 v207, v66, v67
	v_add_f32_e32 v208, v68, v69
	v_add_f32_e32 v209, v70, v71
	v_add_f32_e32 v210, v72, v73
	v_add_f32_e32 v211, v74, v75
	v_add_f32_e32 v212, v76, v77
	v_add_f32_e32 v213, v78, v79
	v_add_f32_e32 v206, v206, v207
	v_add_f32_e32 v208, v208, v209
	v_add_f32_e32 v210, v210, v211
	v_add_f32_e32 v212, v212, v213
	v_add_f32_e32 v206, v206, v208
	v_add_f32_e32 v210, v210, v212
	v_add_f32_e32 v206, v206, v210
	v_add_f32_e32 v251, v251, v206
	v_cvt_pk_bf16_f32 v206, v64, v65
	v_cvt_pk_bf16_f32 v207, v66, v67
	v_cvt_pk_bf16_f32 v208, v68, v69
	v_cvt_pk_bf16_f32 v209, v70, v71
	v_cvt_pk_bf16_f32 v210, v72, v73
	v_cvt_pk_bf16_f32 v211, v74, v75
	v_cvt_pk_bf16_f32 v212, v76, v77
	v_cvt_pk_bf16_f32 v213, v78, v79
	s_waitcnt lgkmcnt(3)
	v_mfma_f32_32x32x16_bf16 v[48:63], v[198:201], v[232:235], v[48:63]
	s_waitcnt lgkmcnt(2)
	v_mfma_f32_32x32x16_bf16 v[32:47], v[198:201], v[236:239], v[32:47]
	v_mfma_f32_32x32x16_bf16 v[16:31], v[206:209], v[232:235], v[16:31]
	v_mfma_f32_32x32x16_bf16 v[0:15], v[206:209], v[236:239], v[0:15]
	s_waitcnt lgkmcnt(1)
	v_mfma_f32_32x32x16_bf16 v[48:63], v[202:205], v[240:243], v[48:63]
	s_waitcnt lgkmcnt(0)
	v_mfma_f32_32x32x16_bf16 v[32:47], v[202:205], v[244:247], v[32:47]
	v_mfma_f32_32x32x16_bf16 v[16:31], v[210:213], v[240:243], v[16:31]
	v_mfma_f32_32x32x16_bf16 v[0:15], v[210:213], v[244:247], v[0:15]
	v_lshl_add_u64 v[194:195], v[194:195], 0, s[94:95]
	v_lshl_add_u64 v[196:197], v[196:197], 0, s[84:85]
	s_cmp_ge_u32 s45, s41
	s_cbranch_scc1 .Lgq_exit
	s_add_i32 s45, s45, 2

.Lgq_nold15:
	ds_read_b128 v[232:235], v227 offset:8192
	ds_read_b128 v[236:239], v227 offset:12288
	ds_read_b128 v[240:243], v228 offset:8192
	ds_read_b128 v[244:247], v228 offset:12288
	v_max3_f32 v252, v80, v81, v82
	v_max3_f32 v252, v252, v83, v84
	v_max3_f32 v252, v252, v85, v86
	v_max3_f32 v252, v252, v87, v88
	v_max3_f32 v252, v252, v89, v90
	v_max3_f32 v252, v252, v91, v92
	v_max3_f32 v252, v252, v93, v94
	v_max_f32_e32 v252, v252, v95
	v_mov_b32_e32 v248, v252
	s_nop 1
	v_permlane32_swap_b32_e32 v252, v248
	v_max_f32_e32 v252, v252, v248
	v_max3_f32 v253, v64, v65, v66
	v_max3_f32 v253, v253, v67, v68
	v_max3_f32 v253, v253, v69, v70
	v_max3_f32 v253, v253, v71, v72
	v_max3_f32 v253, v253, v73, v74
	v_max3_f32 v253, v253, v75, v76
	v_max3_f32 v253, v253, v77, v78
	v_max_f32_e32 v253, v253, v79
	v_mov_b32_e32 v249, v253
	s_nop 1
	v_permlane32_swap_b32_e32 v253, v249
	v_max_f32_e32 v253, v253, v249
	v_cmp_lt_f32_e32 vcc, s97, v252
	s_cbranch_vccnz .Lgq_rare17

.Lgq_back18:
	v_exp_f32_e32 v80, v80
	v_exp_f32_e32 v81, v81
	v_exp_f32_e32 v82, v82
	v_exp_f32_e32 v83, v83
	v_exp_f32_e32 v84, v84
	v_exp_f32_e32 v85, v85
	v_exp_f32_e32 v86, v86
	v_exp_f32_e32 v87, v87
	v_exp_f32_e32 v88, v88
	v_exp_f32_e32 v89, v89
	v_exp_f32_e32 v90, v90
	v_exp_f32_e32 v91, v91
	v_exp_f32_e32 v92, v92
	v_exp_f32_e32 v93, v93
	v_exp_f32_e32 v94, v94
	v_exp_f32_e32 v95, v95
	v_add_f32_e32 v104, v80, v81
	v_add_f32_e32 v105, v82, v83
	v_add_f32_e32 v106, v84, v85
	v_add_f32_e32 v107, v86, v87
	v_add_f32_e32 v108, v88, v89
	v_add_f32_e32 v109, v90, v91
	v_add_f32_e32 v110, v92, v93
	v_add_f32_e32 v111, v94, v95
	v_add_f32_e32 v104, v104, v105
	v_add_f32_e32 v106, v106, v107
	v_add_f32_e32 v108, v108, v109
	v_add_f32_e32 v110, v110, v111
	v_add_f32_e32 v104, v104, v106
	v_add_f32_e32 v108, v108, v110
	v_add_f32_e32 v104, v104, v108
	v_add_f32_e32 v250, v250, v104
	v_cvt_pk_bf16_f32 v96, v80, v81
	v_cvt_pk_bf16_f32 v97, v82, v83
	v_cvt_pk_bf16_f32 v98, v84, v85
	v_cvt_pk_bf16_f32 v99, v86, v87
	v_cvt_pk_bf16_f32 v100, v88, v89
	v_cvt_pk_bf16_f32 v101, v90, v91
	v_cvt_pk_bf16_f32 v102, v92, v93
	v_cvt_pk_bf16_f32 v103, v94, v95
	v_exp_f32_e32 v64, v64
	v_exp_f32_e32 v65, v65
	v_exp_f32_e32 v66, v66
	v_exp_f32_e32 v67, v67
	v_exp_f32_e32 v68, v68
	v_exp_f32_e32 v69, v69
	v_exp_f32_e32 v70, v70
	v_exp_f32_e32 v71, v71
	v_exp_f32_e32 v72, v72
	v_exp_f32_e32 v73, v73
	v_exp_f32_e32 v74, v74
	v_exp_f32_e32 v75, v75
	v_exp_f32_e32 v76, v76
	v_exp_f32_e32 v77, v77
	v_exp_f32_e32 v78, v78
	v_exp_f32_e32 v79, v79
	v_add_f32_e32 v104, v64, v65
	v_add_f32_e32 v105, v66, v67
	v_add_f32_e32 v106, v68, v69
	v_add_f32_e32 v107, v70, v71
	v_add_f32_e32 v108, v72, v73
	v_add_f32_e32 v109, v74, v75
	v_add_f32_e32 v110, v76, v77
	v_add_f32_e32 v111, v78, v79
	v_add_f32_e32 v104, v104, v105
	v_add_f32_e32 v106, v106, v107
	v_add_f32_e32 v108, v108, v109
	v_add_f32_e32 v110, v110, v111
	v_add_f32_e32 v104, v104, v106
	v_add_f32_e32 v108, v108, v110
	v_add_f32_e32 v104, v104, v108
	v_add_f32_e32 v251, v251, v104
	v_cvt_pk_bf16_f32 v104, v64, v65
	v_cvt_pk_bf16_f32 v105, v66, v67
	v_cvt_pk_bf16_f32 v106, v68, v69
	v_cvt_pk_bf16_f32 v107, v70, v71
	v_cvt_pk_bf16_f32 v108, v72, v73
	v_cvt_pk_bf16_f32 v109, v74, v75
	v_cvt_pk_bf16_f32 v110, v76, v77
	v_cvt_pk_bf16_f32 v111, v78, v79
	s_waitcnt lgkmcnt(7)
	v_mfma_f32_32x32x16_bf16 v[80:95], v[198:201], v[112:115], v[152:167]
	s_waitcnt lgkmcnt(6)
	v_mfma_f32_32x32x16_bf16 v[80:95], v[202:205], v[116:119], v[80:95]
	s_waitcnt lgkmcnt(5)
	v_mfma_f32_32x32x16_bf16 v[80:95], v[206:209], v[124:127], v[80:95]
	s_waitcnt lgkmcnt(4)
	v_mfma_f32_32x32x16_bf16 v[80:95], v[210:213], v[128:131], v[80:95]
	v_mfma_f32_32x32x16_bf16 v[64:79], v[198:201], v[132:135], v[168:183]
	v_mfma_f32_32x32x16_bf16 v[64:79], v[202:205], v[136:139], v[64:79]
	v_mfma_f32_32x32x16_bf16 v[64:79], v[206:209], v[140:143], v[64:79]
	v_mfma_f32_32x32x16_bf16 v[64:79], v[210:213], v[144:147], v[64:79]
	s_waitcnt lgkmcnt(3)
	v_mfma_f32_32x32x16_bf16 v[48:63], v[96:99], v[232:235], v[48:63]
	s_waitcnt lgkmcnt(2)
	v_mfma_f32_32x32x16_bf16 v[32:47], v[96:99], v[236:239], v[32:47]
	v_mfma_f32_32x32x16_bf16 v[16:31], v[104:107], v[232:235], v[16:31]
	v_mfma_f32_32x32x16_bf16 v[0:15], v[104:107], v[236:239], v[0:15]
	s_nop 1
	v_max3_f32 v252, v80, v81, v82
	v_max3_f32 v252, v252, v83, v84
	v_max3_f32 v252, v252, v85, v86
	v_max3_f32 v252, v252, v87, v88
	v_max3_f32 v252, v252, v89, v90
	v_max3_f32 v252, v252, v91, v92
	v_max3_f32 v252, v252, v93, v94
	v_max_f32_e32 v252, v252, v95
	v_mov_b32_e32 v248, v252
	s_nop 1
	v_permlane32_swap_b32_e32 v252, v248
	v_max_f32_e32 v252, v252, v248
	s_waitcnt lgkmcnt(1)
	v_mfma_f32_32x32x16_bf16 v[48:63], v[100:103], v[240:243], v[48:63]
	s_waitcnt lgkmcnt(0)
	v_mfma_f32_32x32x16_bf16 v[32:47], v[100:103], v[244:247], v[32:47]
	v_mfma_f32_32x32x16_bf16 v[16:31], v[108:111], v[240:243], v[16:31]
	v_mfma_f32_32x32x16_bf16 v[0:15], v[108:111], v[244:247], v[0:15]
	ds_read_b128 v[232:235], v229 offset:8192
	ds_read_b128 v[236:239], v229 offset:12288
	ds_read_b128 v[240:243], v230 offset:8192
	ds_read_b128 v[244:247], v230 offset:12288
	v_max3_f32 v253, v64, v65, v66
	v_max3_f32 v253, v253, v67, v68
	v_max3_f32 v253, v253, v69, v70
	v_max3_f32 v253, v253, v71, v72
	v_max3_f32 v253, v253, v73, v74
	v_max3_f32 v253, v253, v75, v76
	v_max3_f32 v253, v253, v77, v78
	v_max_f32_e32 v253, v253, v79
	v_mov_b32_e32 v249, v253
	s_nop 1
	v_permlane32_swap_b32_e32 v253, v249
	v_max_f32_e32 v253, v253, v249
	v_cmp_lt_f32_e32 vcc, s97, v252
	s_cbranch_vccnz .Lgq_rare21

; __device__ __forceinline__ void attn_core_gqa2(LAS unsigned char* lds, const bf16* __restrict__ Qw, const bf16* __restrict__ Kg, const bf16* __restrict__ Vtg,
;                                                int N, f32x16 (&o)[2][2], const int wave_s) {
;     ...
;     for (int t = 0; t < NT; t += 2) { TILE2(0, t); TILE2(1, t + 1); }
.Lgq_back31:
	v_exp_f32_e32 v80, v80
	v_exp_f32_e32 v81, v81
	v_exp_f32_e32 v82, v82
	v_exp_f32_e32 v83, v83
	v_exp_f32_e32 v84, v84
	v_exp_f32_e32 v85, v85
	v_exp_f32_e32 v86, v86
	v_exp_f32_e32 v87, v87
	v_exp_f32_e32 v88, v88
	v_exp_f32_e32 v89, v89
	v_exp_f32_e32 v90, v90
	v_exp_f32_e32 v91, v91
	v_exp_f32_e32 v92, v92
	v_exp_f32_e32 v93, v93
	v_exp_f32_e32 v94, v94
	v_exp_f32_e32 v95, v95
	v_add_f32_e32 v206, v80, v81
	v_add_f32_e32 v207, v82, v83
	v_add_f32_e32 v208, v84, v85
	v_add_f32_e32 v209, v86, v87
	v_add_f32_e32 v210, v88, v89
	v_add_f32_e32 v211, v90, v91
	v_add_f32_e32 v212, v92, v93
	v_add_f32_e32 v213, v94, v95
	v_add_f32_e32 v206, v206, v207
	v_add_f32_e32 v208, v208, v209
	v_add_f32_e32 v210, v210, v211
	v_add_f32_e32 v212, v212, v213
	v_add_f32_e32 v206, v206, v208
	v_add_f32_e32 v210, v210, v212
	v_add_f32_e32 v206, v206, v210
	v_add_f32_e32 v250, v250, v206
	v_cvt_pk_bf16_f32 v198, v80, v81
	v_cvt_pk_bf16_f32 v199, v82, v83
	v_cvt_pk_bf16_f32 v200, v84, v85
	v_cvt_pk_bf16_f32 v201, v86, v87
	v_cvt_pk_bf16_f32 v202, v88, v89
	v_cvt_pk_bf16_f32 v203, v90, v91
	v_cvt_pk_bf16_f32 v204, v92, v93
	v_cvt_pk_bf16_f32 v205, v94, v95
	v_exp_f32_e32 v64, v64
	v_exp_f32_e32 v65, v65
	v_exp_f32_e32 v66, v66
	v_exp_f32_e32 v67, v67
	v_exp_f32_e32 v68, v68
	v_exp_f32_e32 v69, v69
	v_exp_f32_e32 v70, v70
	v_exp_f32_e32 v71, v71
	v_exp_f32_e32 v72, v72
	v_exp_f32_e32 v73, v73
	v_exp_f32_e32 v74, v74
	v_exp_f32_e32 v75, v75
	v_exp_f32_e32 v76, v76
	v_exp_f32_e32 v77, v77
	v_exp_f32_e32 v78, v78
	v_exp_f32_e32 v79, v79
	v_add_f32_e32 v206, v64, v65
	v_add_f32_e32 v207, v66, v67
	v_add_f32_e32 v208, v68, v69
	v_add_f32_e32 v209, v70, v71
	v_add_f32_e32 v210, v72, v73
	v_add_f32_e32 v211, v74, v75
	v_add_f32_e32 v212, v76, v77
	v_add_f32_e32 v213, v78, v79
	v_add_f32_e32 v206, v206, v207
	v_add_f32_e32 v208, v208, v209
	v_add_f32_e32 v210, v210, v211
	v_add_f32_e32 v212, v212, v213
	v_add_f32_e32 v206, v206, v208
	v_add_f32_e32 v210, v210, v212
	v_add_f32_e32 v206, v206, v210
	v_add_f32_e32 v251, v251, v206
	v_cvt_pk_bf16_f32 v206, v64, v65
	v_cvt_pk_bf16_f32 v207, v66, v67
	v_cvt_pk_bf16_f32 v208, v68, v69
	v_cvt_pk_bf16_f32 v209, v70, v71
	v_cvt_pk_bf16_f32 v210, v72, v73
	v_cvt_pk_bf16_f32 v211, v74, v75
	v_cvt_pk_bf16_f32 v212, v76, v77
	v_cvt_pk_bf16_f32 v213, v78, v79
	s_waitcnt lgkmcnt(3)
	v_mfma_f32_32x32x16_bf16 v[48:63], v[198:201], v[232:235], v[48:63]
	s_waitcnt lgkmcnt(2)
	v_mfma_f32_32x32x16_bf16 v[32:47], v[198:201], v[236:239], v[32:47]
	v_mfma_f32_32x32x16_bf16 v[16:31], v[206:209], v[232:235], v[16:31]
	v_mfma_f32_32x32x16_bf16 v[0:15], v[206:209], v[236:239], v[0:15]
	s_waitcnt lgkmcnt(1)
	v_mfma_f32_32x32x16_bf16 v[48:63], v[202:205], v[240:243], v[48:63]
	s_waitcnt lgkmcnt(0)
	v_mfma_f32_32x32x16_bf16 v[32:47], v[202:205], v[244:247], v[32:47]
	v_mfma_f32_32x32x16_bf16 v[16:31], v[210:213], v[240:243], v[16:31]
	v_mfma_f32_32x32x16_bf16 v[0:15], v[210:213], v[244:247], v[0:15]
	v_lshl_add_u64 v[194:195], v[194:195], 0, s[94:95]
	v_lshl_add_u64 v[196:197], v[196:197], 0, s[84:85]
	s_cmp_ge_u32 s45, s41
	s_cbranch_scc1 .Lgq_exit
	s_add_i32 s45, s45, 2
	s_branch .Lgq_loop
.Lgq_rare3:
	s_nop 15
	v_max_f32_e32 v248, v252, v252
	v_max_f32_e32 v248, 0, v248
	v_add_f32_e32 v231, v231, v248
	v_sub_f32_e32 v80, v80, v248
	v_sub_f32_e32 v81, v81, v248
	v_sub_f32_e32 v82, v82, v248
	v_sub_f32_e32 v83, v83, v248
	v_sub_f32_e32 v84, v84, v248
	v_sub_f32_e32 v85, v85, v248
	v_sub_f32_e32 v86, v86, v248
	v_sub_f32_e32 v87, v87, v248
	v_sub_f32_e32 v88, v88, v248
	v_sub_f32_e32 v89, v89, v248
	v_sub_f32_e32 v90, v90, v248
	v_sub_f32_e32 v91, v91, v248
	v_sub_f32_e32 v92, v92, v248
	v_sub_f32_e32 v93, v93, v248
	v_sub_f32_e32 v94, v94, v248
	v_sub_f32_e32 v95, v95, v248
	v_exp_f32_e64 v249, -v248
	s_nop 0
	ds_write_b32 v222, v249
	ds_read_b128 v[198:201], v221
	ds_read_b128 v[202:205], v221 offset:32
	ds_read_b128 v[206:209], v221 offset:64
	ds_read_b128 v[210:213], v221 offset:96
	v_mul_f32_e32 v250, v250, v249
	s_waitcnt lgkmcnt(0)
	v_pk_mul_f32 v[48:49], v[48:49], v[198:199]
	v_pk_mul_f32 v[50:51], v[50:51], v[200:201]
	v_pk_mul_f32 v[52:53], v[52:53], v[202:203]
	v_pk_mul_f32 v[54:55], v[54:55], v[204:205]
	v_pk_mul_f32 v[56:57], v[56:57], v[206:207]
	v_pk_mul_f32 v[58:59], v[58:59], v[208:209]
	v_pk_mul_f32 v[60:61], v[60:61], v[210:211]
	v_pk_mul_f32 v[62:63], v[62:63], v[212:213]
	v_pk_mul_f32 v[32:33], v[32:33], v[198:199]
	v_pk_mul_f32 v[34:35], v[34:35], v[200:201]
	v_pk_mul_f32 v[36:37], v[36:37], v[202:203]
	v_pk_mul_f32 v[38:39], v[38:39], v[204:205]
	v_pk_mul_f32 v[40:41], v[40:41], v[206:207]
	v_pk_mul_f32 v[42:43], v[42:43], v[208:209]
	v_pk_mul_f32 v[44:45], v[44:45], v[210:211]
	v_pk_mul_f32 v[46:47], v[46:47], v[212:213]
	v_xor_b32_e32 v152, 0x80000000, v231
	v_mov_b32_e32 v153, v152
	v_mov_b32_e32 v154, v152
	v_mov_b32_e32 v155, v152
	v_mov_b32_e32 v156, v152
	v_mov_b32_e32 v157, v152
	v_mov_b32_e32 v158, v152
	v_mov_b32_e32 v159, v152
	v_mov_b32_e32 v160, v152
	v_mov_b32_e32 v161, v152
	v_mov_b32_e32 v162, v152
	v_mov_b32_e32 v163, v152
	v_mov_b32_e32 v164, v152
	v_mov_b32_e32 v165, v152
	v_mov_b32_e32 v166, v152
	v_mov_b32_e32 v167, v152
	s_branch .Lgq_back2
.Lgq_rare5:
	s_nop 15
	v_max_f32_e32 v248, v253, v253
	v_max_f32_e32 v248, 0, v248
	v_add_f32_e32 v223, v223, v248
	v_sub_f32_e32 v64, v64, v248
	v_sub_f32_e32 v65, v65, v248
	v_sub_f32_e32 v66, v66, v248
	v_sub_f32_e32 v67, v67, v248
	v_sub_f32_e32 v68, v68, v248
	v_sub_f32_e32 v69, v69, v248
	v_sub_f32_e32 v70, v70, v248
	v_sub_f32_e32 v71, v71, v248
	v_sub_f32_e32 v72, v72, v248
	v_sub_f32_e32 v73, v73, v248
	v_sub_f32_e32 v74, v74, v248
	v_sub_f32_e32 v75, v75, v248
	v_sub_f32_e32 v76, v76, v248
	v_sub_f32_e32 v77, v77, v248
	v_sub_f32_e32 v78, v78, v248
	v_sub_f32_e32 v79, v79, v248
	v_exp_f32_e64 v249, -v248
	s_nop 0
	ds_write_b32 v222, v249
	ds_read_b128 v[198:201], v221
	ds_read_b128 v[202:205], v221 offset:32
	ds_read_b128 v[206:209], v221 offset:64
	ds_read_b128 v[210:213], v221 offset:96
	v_mul_f32_e32 v251, v251, v249
	s_waitcnt lgkmcnt(0)
	v_pk_mul_f32 v[16:17], v[16:17], v[198:199]
	v_pk_mul_f32 v[18:19], v[18:19], v[200:201]
	v_pk_mul_f32 v[20:21], v[20:21], v[202:203]
	v_pk_mul_f32 v[22:23], v[22:23], v[204:205]
	v_pk_mul_f32 v[24:25], v[24:25], v[206:207]
	v_pk_mul_f32 v[26:27], v[26:27], v[208:209]
	v_pk_mul_f32 v[28:29], v[28:29], v[210:211]
	v_pk_mul_f32 v[30:31], v[30:31], v[212:213]
	v_pk_mul_f32 v[0:1], v[0:1], v[198:199]
	v_pk_mul_f32 v[2:3], v[2:3], v[200:201]
	v_pk_mul_f32 v[4:5], v[4:5], v[202:203]
	v_pk_mul_f32 v[6:7], v[6:7], v[204:205]
	v_pk_mul_f32 v[8:9], v[8:9], v[206:207]
	v_pk_mul_f32 v[10:11], v[10:11], v[208:209]
	v_pk_mul_f32 v[12:13], v[12:13], v[210:211]
	v_pk_mul_f32 v[14:15], v[14:15], v[212:213]
	v_xor_b32_e32 v168, 0x80000000, v223
	v_mov_b32_e32 v169, v168
	v_mov_b32_e32 v170, v168
	v_mov_b32_e32 v171, v168
	v_mov_b32_e32 v172, v168
	v_mov_b32_e32 v173, v168
	v_mov_b32_e32 v174, v168
	v_mov_b32_e32 v175, v168
	v_mov_b32_e32 v176, v168
	v_mov_b32_e32 v177, v168
	v_mov_b32_e32 v178, v168
	v_mov_b32_e32 v179, v168
	v_mov_b32_e32 v180, v168
	v_mov_b32_e32 v181, v168
	v_mov_b32_e32 v182, v168
	v_mov_b32_e32 v183, v168
	s_branch .Lgq_back4
.Lgq_rare8:
	s_nop 15
	v_max_f32_e32 v248, v252, v252
	v_max_f32_e32 v248, 0, v248
	v_add_f32_e32 v231, v231, v248
	v_sub_f32_e32 v80, v80, v248
	v_sub_f32_e32 v81, v81, v248
	v_sub_f32_e32 v82, v82, v248
	v_sub_f32_e32 v83, v83, v248
	v_sub_f32_e32 v84, v84, v248
	v_sub_f32_e32 v85, v85, v248
	v_sub_f32_e32 v86, v86, v248
	v_sub_f32_e32 v87, v87, v248
	v_sub_f32_e32 v88, v88, v248
	v_sub_f32_e32 v89, v89, v248
	v_sub_f32_e32 v90, v90, v248
	v_sub_f32_e32 v91, v91, v248
	v_sub_f32_e32 v92, v92, v248
	v_sub_f32_e32 v93, v93, v248
	v_sub_f32_e32 v94, v94, v248
	v_sub_f32_e32 v95, v95, v248
	v_exp_f32_e64 v249, -v248
	s_nop 0
	ds_write_b32 v222, v249
	ds_read_b128 v[96:99], v221
	ds_read_b128 v[100:103], v221 offset:32
	ds_read_b128 v[104:107], v221 offset:64
	ds_read_b128 v[108:111], v221 offset:96
	v_mul_f32_e32 v250, v250, v249
	s_waitcnt lgkmcnt(0)
	v_pk_mul_f32 v[48:49], v[48:49], v[96:97]
	v_pk_mul_f32 v[50:51], v[50:51], v[98:99]
	v_pk_mul_f32 v[52:53], v[52:53], v[100:101]
	v_pk_mul_f32 v[54:55], v[54:55], v[102:103]
	v_pk_mul_f32 v[56:57], v[56:57], v[104:105]
	v_pk_mul_f32 v[58:59], v[58:59], v[106:107]
	v_pk_mul_f32 v[60:61], v[60:61], v[108:109]
	v_pk_mul_f32 v[62:63], v[62:63], v[110:111]
	v_pk_mul_f32 v[32:33], v[32:33], v[96:97]
	v_pk_mul_f32 v[34:35], v[34:35], v[98:99]
	v_pk_mul_f32 v[36:37], v[36:37], v[100:101]
	v_pk_mul_f32 v[38:39], v[38:39], v[102:103]
	v_pk_mul_f32 v[40:41], v[40:41], v[104:105]
	v_pk_mul_f32 v[42:43], v[42:43], v[106:107]
	v_pk_mul_f32 v[44:45], v[44:45], v[108:109]
	v_pk_mul_f32 v[46:47], v[46:47], v[110:111]
	v_xor_b32_e32 v152, 0x80000000, v231
	v_mov_b32_e32 v153, v152
	v_mov_b32_e32 v154, v152
	v_mov_b32_e32 v155, v152
	v_mov_b32_e32 v156, v152
	v_mov_b32_e32 v157, v152
	v_mov_b32_e32 v158, v152
	v_mov_b32_e32 v159, v152
	v_mov_b32_e32 v160, v152
	v_mov_b32_e32 v161, v152
	v_mov_b32_e32 v162, v152
	v_mov_b32_e32 v163, v152
	v_mov_b32_e32 v164, v152
	v_mov_b32_e32 v165, v152
	v_mov_b32_e32 v166, v152
	v_mov_b32_e32 v167, v152
	s_branch .Lgq_back7
.Lgq_rare10:
	s_nop 15
	v_max_f32_e32 v248, v253, v253
	v_max_f32_e32 v248, 0, v248
	v_add_f32_e32 v223, v223, v248
	v_sub_f32_e32 v64, v64, v248
	v_sub_f32_e32 v65, v65, v248
	v_sub_f32_e32 v66, v66, v248
	v_sub_f32_e32 v67, v67, v248
	v_sub_f32_e32 v68, v68, v248
	v_sub_f32_e32 v69, v69, v248
	v_sub_f32_e32 v70, v70, v248
	v_sub_f32_e32 v71, v71, v248
	v_sub_f32_e32 v72, v72, v248
	v_sub_f32_e32 v73, v73, v248
	v_sub_f32_e32 v74, v74, v248
	v_sub_f32_e32 v75, v75, v248
	v_sub_f32_e32 v76, v76, v248
	v_sub_f32_e32 v77, v77, v248
	v_sub_f32_e32 v78, v78, v248
	v_sub_f32_e32 v79, v79, v248
	v_exp_f32_e64 v249, -v248
	s_nop 0
	ds_write_b32 v222, v249
	ds_read_b128 v[96:99], v221
	ds_read_b128 v[100:103], v221 offset:32
	ds_read_b128 v[104:107], v221 offset:64
	ds_read_b128 v[108:111], v221 offset:96
	v_mul_f32_e32 v251, v251, v249
	s_waitcnt lgkmcnt(0)
	v_pk_mul_f32 v[16:17], v[16:17], v[96:97]
	v_pk_mul_f32 v[18:19], v[18:19], v[98:99]
	v_pk_mul_f32 v[20:21], v[20:21], v[100:101]
	v_pk_mul_f32 v[22:23], v[22:23], v[102:103]
	v_pk_mul_f32 v[24:25], v[24:25], v[104:105]
	v_pk_mul_f32 v[26:27], v[26:27], v[106:107]
	v_pk_mul_f32 v[28:29], v[28:29], v[108:109]
	v_pk_mul_f32 v[30:31], v[30:31], v[110:111]
	v_pk_mul_f32 v[0:1], v[0:1], v[96:97]
	v_pk_mul_f32 v[2:3], v[2:3], v[98:99]
	v_pk_mul_f32 v[4:5], v[4:5], v[100:101]
	v_pk_mul_f32 v[6:7], v[6:7], v[102:103]
	v_pk_mul_f32 v[8:9], v[8:9], v[104:105]
	v_pk_mul_f32 v[10:11], v[10:11], v[106:107]
	v_pk_mul_f32 v[12:13], v[12:13], v[108:109]
	v_pk_mul_f32 v[14:15], v[14:15], v[110:111]
	v_xor_b32_e32 v168, 0x80000000, v223
	v_mov_b32_e32 v169, v168
	v_mov_b32_e32 v170, v168
	v_mov_b32_e32 v171, v168
	v_mov_b32_e32 v172, v168
	v_mov_b32_e32 v173, v168
	v_mov_b32_e32 v174, v168
	v_mov_b32_e32 v175, v168
	v_mov_b32_e32 v176, v168
	v_mov_b32_e32 v177, v168
	v_mov_b32_e32 v178, v168
	v_mov_b32_e32 v179, v168
	v_mov_b32_e32 v180, v168
	v_mov_b32_e32 v181, v168
	v_mov_b32_e32 v182, v168
	v_mov_b32_e32 v183, v168
	s_branch .Lgq_back9

; __device__ __forceinline__ float xsum32(float v) { auto rr = __builtin_amdgcn_permlane32_swap(__float_as_uint(v), __float_as_uint(v), false, false); return __uint_as_float(rr[0]) + __uint_as_float(rr[1]); }
; __device__ __forceinline__ int crow(int r, int hi) { return (r & 3) + 8 * (r >> 2) + 4 * hi; }
; __device__ __forceinline__ void attn_core_gqa2(LAS unsigned char* lds, const bf16* __restrict__ Qw, const bf16* __restrict__ Kg, const bf16* __restrict__ Vtg,
;                                                int N, f32x16 (&o)[2][2], const int wave_s) {
;     ...
; #pragma unroll
;     for (int h = 0; h < 2; ++h) {
;         const float lt = xsum32(l[h]);
;         wsf[r32] = 1.f / lt;
; #pragma unroll
;         for (int r = 0; r < 16; ++r) { const float fr = wsf[crow(r, hi)]; o[h][0][r] *= fr; o[h][1][r] *= fr; }
;     }
.Lgq_exit:
	v_mov_b32_e32 v173, v250
	v_mov_b32_e32 v202, v251
	s_branch .LBB0_295
